# adds nt hint on the once-read f32 weight loads of the weight-conversion prologue
# speedup vs baseline: 1.0118x; 1.0118x over previous
.LBB0_11:
	s_cmpk_gt_i32 s50, 0x3ff
	s_mov_b64 s[4:5], -1
	s_cbranch_scc0 .LBB0_101
	s_cmpk_gt_u32 s50, 0x5ff
	s_cbranch_scc0 .LBB0_98
	s_cmpk_gt_u32 s50, 0x10ff
	s_cbranch_scc0 .LBB0_87
	s_cmpk_gt_u32 s50, 0x167f
	s_cbranch_scc0 .LBB0_84
	s_cmpk_gt_u32 s50, 0x197f
	s_cbranch_scc0 .LBB0_57
	s_cmpk_gt_u32 s50, 0x1f7f
	s_cbranch_scc0 .LBB0_38
	s_cmpk_gt_u32 s50, 0x217f
	s_cbranch_scc0 .LBB0_35
	s_cmpk_gt_u32 s50, 0x2c7f
	s_cbranch_scc0 .LBB0_24
	s_cmpk_gt_u32 s50, 0x31ff
	s_cbranch_scc0 .LBB0_21
	s_add_i32 s4, s50, 0xffffce00
	s_cmp_lt_u32 s4, 64
	s_cselect_b32 s4, 48, 64
	s_add_u32 s4, s0, s4
	s_addc_u32 s5, s1, 0
	s_load_dwordx2 s[4:5], s[4:5], 0x0
	s_lshl_b32 s14, s50, 13
	s_and_b32 s26, s14, 0x70000
	v_mov_b32_e32 v73, v37
	v_add_u32_e32 v75, 0x848, v87
	s_waitcnt lgkmcnt(0)
	s_add_u32 s14, s4, s26
	s_addc_u32 s5, s5, 0
	s_add_i32 s4, s35, 0xffff9c00
	s_and_b32 s15, s9, 0x60
	s_and_b32 s4, s4, 0x7fffff80
	s_or_b32 s4, s4, s15
	s_and_b32 s51, s37, 64
	s_lshl_b32 s15, s15, 2
	s_add_u32 s14, s14, s15
	v_or_b32_e32 v4, s51, v1
	s_addc_u32 s15, s5, 0
	v_lshl_add_u64 v[2:3], s[14:15], 0, v[72:73]
	v_lshlrev_b32_e32 v36, 9, v4
	v_lshl_add_u64 v[30:31], v[2:3], 0, v[36:37]
	v_add_co_u32_e32 v10, vcc, s39, v30
	global_load_dwordx4 v[2:5], v[30:31], off nt
	s_nop 0
	v_addc_co_u32_e32 v11, vcc, 0, v31, vcc
	v_add_co_u32_e32 v18, vcc, s42, v30
	global_load_dwordx4 v[6:9], v[10:11], off offset:-4096 nt
	s_nop 0
	global_load_dwordx4 v[10:13], v[10:11], off nt
	v_addc_co_u32_e32 v19, vcc, 0, v31, vcc
	v_add_co_u32_e32 v26, vcc, s43, v30
	global_load_dwordx4 v[14:17], v[18:19], off offset:-4096 nt
	s_nop 0
	global_load_dwordx4 v[18:21], v[18:19], off nt
	v_addc_co_u32_e32 v27, vcc, 0, v31, vcc
	v_add_co_u32_e32 v30, vcc, s46, v30
	global_load_dwordx4 v[22:25], v[26:27], off offset:-4096 nt
	s_nop 0
	global_load_dwordx4 v[26:29], v[26:27], off nt
	v_addc_co_u32_e32 v31, vcc, 0, v31, vcc
	global_load_dwordx4 v[30:33], v[30:31], off nt
	v_add_u32_e32 v36, 0x428, v87
	v_add_u32_e32 v73, 0x840, v87
	v_add_u32_e32 v76, 0xc60, v87
	v_add_u32_e32 v89, 0xc68, v87
	v_add_u32_e32 v90, 0x1080, v87
	v_add_u32_e32 v91, 0x1088, v87
	v_add_u32_e32 v92, 0x14a0, v87
	v_add_u32_e32 v93, 0x14a8, v87
	v_add_u32_e32 v94, 0x18c0, v87
	v_add_u32_e32 v95, 0x18c8, v87
	v_add_u32_e32 v96, 0x1ce0, v87
	v_add_u32_e32 v97, 0x1ce8, v87
	s_waitcnt vmcnt(7)
	v_pk_mul_f32 v[2:3], v[2:3], s[8:9] op_sel_hi:[1,0]
	v_pk_mul_f32 v[4:5], v[4:5], s[8:9] op_sel_hi:[1,0]
	ds_write2_b32 v87, v2, v3 offset1:1
	ds_write2_b32 v87, v4, v5 offset0:2 offset1:3
	s_waitcnt vmcnt(6)
	v_pk_mul_f32 v[2:3], v[6:7], s[8:9] op_sel_hi:[1,0]
	v_pk_mul_f32 v[4:5], v[8:9], s[8:9] op_sel_hi:[1,0]
	s_waitcnt vmcnt(5)
	v_pk_mul_f32 v[6:7], v[10:11], s[8:9] op_sel_hi:[1,0]
	v_pk_mul_f32 v[8:9], v[12:13], s[8:9] op_sel_hi:[1,0]
	s_waitcnt vmcnt(4)
	v_pk_mul_f32 v[10:11], v[14:15], s[8:9] op_sel_hi:[1,0]
	v_pk_mul_f32 v[12:13], v[16:17], s[8:9] op_sel_hi:[1,0]
	s_waitcnt vmcnt(3)
	v_pk_mul_f32 v[14:15], v[18:19], s[8:9] op_sel_hi:[1,0]
	v_pk_mul_f32 v[16:17], v[20:21], s[8:9] op_sel_hi:[1,0]
	s_waitcnt vmcnt(2)
	v_pk_mul_f32 v[18:19], v[22:23], s[8:9] op_sel_hi:[1,0]
	v_pk_mul_f32 v[20:21], v[24:25], s[8:9] op_sel_hi:[1,0]
	s_waitcnt vmcnt(1)
	v_pk_mul_f32 v[22:23], v[26:27], s[8:9] op_sel_hi:[1,0]
	v_pk_mul_f32 v[24:25], v[28:29], s[8:9] op_sel_hi:[1,0]
	s_waitcnt vmcnt(0)
	v_pk_mul_f32 v[26:27], v[30:31], s[8:9] op_sel_hi:[1,0]
	v_pk_mul_f32 v[28:29], v[32:33], s[8:9] op_sel_hi:[1,0]
	ds_write2_b32 v88, v2, v3 offset1:1
	ds_write2_b32 v36, v4, v5 offset1:1
	ds_write2_b32 v73, v6, v7 offset1:1
	ds_write2_b32 v75, v8, v9 offset1:1
	ds_write2_b32 v76, v10, v11 offset1:1
	ds_write2_b32 v89, v12, v13 offset1:1
	ds_write2_b32 v90, v14, v15 offset1:1
	ds_write2_b32 v91, v16, v17 offset1:1
	ds_write2_b32 v92, v18, v19 offset1:1
	ds_write2_b32 v93, v20, v21 offset1:1
	ds_write2_b32 v94, v22, v23 offset1:1
	ds_write2_b32 v95, v24, v25 offset1:1
	ds_write2_b32 v96, v26, v27 offset1:1
	ds_write2_b32 v97, v28, v29 offset1:1
	s_waitcnt lgkmcnt(0)
	ds_read2_b32 v[2:3], v80 offset1:33
	v_lshl_add_u64 v[8:9], v[34:35], 0, s[26:27]
	s_lshl_b32 s26, s51, 1
	s_waitcnt lgkmcnt(0)
	v_cvt_pk_bf16_f32 v2, v2, v3
	ds_read2_b32 v[4:5], v80 offset0:66 offset1:99
	v_mov_b32_e32 v75, v37
	v_lshl_add_u64 v[8:9], v[8:9], 0, s[26:27]
	v_or_b32_e32 v36, s4, v1
	s_waitcnt lgkmcnt(0)
	v_cvt_pk_bf16_f32 v3, v4, v5
	ds_read2_b32 v[4:5], v80 offset0:132 offset1:165
	v_lshl_add_u64 v[8:9], v[8:9], 0, v[74:75]
	v_lshlrev_b64 v[10:11], 8, v[36:37]
	s_waitcnt lgkmcnt(0)
	v_cvt_pk_bf16_f32 v4, v4, v5
	ds_read2_b32 v[6:7], v80 offset0:198 offset1:231
	s_waitcnt lgkmcnt(0)
	v_cvt_pk_bf16_f32 v5, v6, v7
	v_lshl_add_u64 v[10:11], v[8:9], 0, v[10:11]
	ds_read2_b32 v[6:7], v80 offset0:8 offset1:41
	global_store_dwordx4 v[10:11], v[2:5], off
	v_or_b32_e32 v36, s4, v77
	v_lshlrev_b64 v[10:11], 8, v[36:37]
	s_waitcnt lgkmcnt(0)
	v_cvt_pk_bf16_f32 v2, v6, v7
	ds_read2_b32 v[4:5], v80 offset0:74 offset1:107
	s_waitcnt lgkmcnt(0)
	v_cvt_pk_bf16_f32 v3, v4, v5
	ds_read2_b32 v[4:5], v80 offset0:140 offset1:173
	s_waitcnt lgkmcnt(0)
	v_cvt_pk_bf16_f32 v4, v4, v5
	ds_read2_b32 v[6:7], v80 offset0:206 offset1:239
	s_waitcnt lgkmcnt(0)
	v_cvt_pk_bf16_f32 v5, v6, v7
	v_lshl_add_u64 v[10:11], v[8:9], 0, v[10:11]
	ds_read2_b32 v[6:7], v80 offset0:16 offset1:49
	global_store_dwordx4 v[10:11], v[2:5], off
	v_or_b32_e32 v36, s4, v78
	v_lshlrev_b64 v[10:11], 8, v[36:37]
	s_waitcnt lgkmcnt(0)
	v_cvt_pk_bf16_f32 v2, v6, v7
	ds_read2_b32 v[4:5], v80 offset0:82 offset1:115
	s_waitcnt lgkmcnt(0)
	v_cvt_pk_bf16_f32 v3, v4, v5
	ds_read2_b32 v[4:5], v80 offset0:148 offset1:181
	s_waitcnt lgkmcnt(0)
	v_cvt_pk_bf16_f32 v4, v4, v5
	ds_read2_b32 v[6:7], v80 offset0:214 offset1:247
	s_waitcnt lgkmcnt(0)
	v_cvt_pk_bf16_f32 v5, v6, v7
	v_lshl_add_u64 v[10:11], v[8:9], 0, v[10:11]
	ds_read2_b32 v[6:7], v80 offset0:24 offset1:57
	global_store_dwordx4 v[10:11], v[2:5], off
	v_or_b32_e32 v36, s4, v79
	v_lshlrev_b64 v[10:11], 8, v[36:37]
	s_waitcnt lgkmcnt(0)
	v_cvt_pk_bf16_f32 v2, v6, v7
	ds_read2_b32 v[4:5], v80 offset0:90 offset1:123
	s_waitcnt lgkmcnt(0)
	v_cvt_pk_bf16_f32 v3, v4, v5
	ds_read2_b32 v[4:5], v80 offset0:156 offset1:189
	s_waitcnt lgkmcnt(0)
	v_cvt_pk_bf16_f32 v4, v4, v5
	ds_read2_b32 v[6:7], v80 offset0:222 offset1:255
	s_waitcnt lgkmcnt(0)
	v_cvt_pk_bf16_f32 v5, v6, v7
	v_lshl_add_u64 v[6:7], v[8:9], 0, v[10:11]
	global_store_dwordx4 v[6:7], v[2:5], off
	s_waitcnt lgkmcnt(0)
	s_mov_b64 s[4:5], 0
.LBB0_21:
	s_andn2_b64 vcc, exec, s[4:5]
	s_cbranch_vccnz .LBB0_23
	s_and_b32 s4, s35, 0x7fc0
	s_addk_i32 s4, 0xa700
	s_and_b32 s14, s9, 0x3e0
	v_or_b32_e32 v36, s4, v1
	s_lshl_b32 s26, s14, 2
	v_or_b32_e32 v4, 8, v36
	v_mov_b32_e32 v5, v37
	v_or_b32_e32 v10, 16, v36
	v_mov_b32_e32 v11, v37
	v_or_b32_e32 v12, 24, v36
	v_mov_b32_e32 v13, v37
	v_or_b32_e32 v18, 32, v36
	v_mov_b32_e32 v19, v37
	v_or_b32_e32 v20, 40, v36
	v_mov_b32_e32 v21, v37
	v_lshl_add_u64 v[30:31], v[54:55], 0, s[26:27]
	v_lshlrev_b64 v[2:3], 12, v[36:37]
	v_lshlrev_b64 v[4:5], 12, v[4:5]
	v_lshlrev_b64 v[10:11], 12, v[10:11]
	v_lshlrev_b64 v[12:13], 12, v[12:13]
	v_lshlrev_b64 v[18:19], 12, v[18:19]
	v_lshlrev_b64 v[20:21], 12, v[20:21]
	v_lshl_add_u64 v[2:3], v[30:31], 0, v[2:3]
	v_lshl_add_u64 v[6:7], v[30:31], 0, v[4:5]
	v_lshl_add_u64 v[10:11], v[30:31], 0, v[10:11]
	v_lshl_add_u64 v[14:15], v[30:31], 0, v[12:13]
	v_lshl_add_u64 v[18:19], v[30:31], 0, v[18:19]
	v_lshl_add_u64 v[22:23], v[30:31], 0, v[20:21]
	global_load_dwordx4 v[2:5], v[2:3], off nt
	s_nop 0
	global_load_dwordx4 v[6:9], v[6:7], off nt
	s_nop 0
	global_load_dwordx4 v[10:13], v[10:11], off nt
	s_nop 0
	global_load_dwordx4 v[14:17], v[14:15], off nt
	s_nop 0
	global_load_dwordx4 v[18:21], v[18:19], off nt
	s_nop 0
	global_load_dwordx4 v[22:25], v[22:23], off nt
	v_or_b32_e32 v26, 48, v36
	v_mov_b32_e32 v27, v37
	v_lshlrev_b64 v[26:27], 12, v[26:27]
	v_lshl_add_u64 v[26:27], v[30:31], 0, v[26:27]
	v_or_b32_e32 v36, 56, v36
	global_load_dwordx4 v[26:29], v[26:27], off nt
	v_lshlrev_b64 v[32:33], 12, v[36:37]
	v_lshl_add_u64 v[30:31], v[30:31], 0, v[32:33]
	global_load_dwordx4 v[30:33], v[30:31], off nt
	v_add_u32_e32 v36, 0x428, v87
	v_add_u32_e32 v73, 0x840, v87
	v_add_u32_e32 v75, 0x848, v87
	v_add_u32_e32 v76, 0xc60, v87
	v_add_u32_e32 v89, 0xc68, v87
	v_add_u32_e32 v90, 0x1080, v87
	v_add_u32_e32 v91, 0x1088, v87
	v_add_u32_e32 v92, 0x14a0, v87
	v_add_u32_e32 v93, 0x14a8, v87
	v_add_u32_e32 v94, 0x18c0, v87
	v_add_u32_e32 v95, 0x18c8, v87
	v_add_u32_e32 v96, 0x1ce0, v87
	v_add_u32_e32 v97, 0x1ce8, v87
	s_mov_b32 s5, s27
	s_waitcnt vmcnt(7)
	ds_write2_b32 v87, v2, v3 offset1:1
	ds_write2_b32 v87, v4, v5 offset0:2 offset1:3
	s_waitcnt vmcnt(6)
	ds_write2_b32 v88, v6, v7 offset1:1
	ds_write2_b32 v36, v8, v9 offset1:1
	s_waitcnt vmcnt(5)
	ds_write2_b32 v73, v10, v11 offset1:1
	ds_write2_b32 v75, v12, v13 offset1:1
	s_waitcnt vmcnt(4)
	ds_write2_b32 v76, v14, v15 offset1:1
	ds_write2_b32 v89, v16, v17 offset1:1
	s_waitcnt vmcnt(3)
	ds_write2_b32 v90, v18, v19 offset1:1
	ds_write2_b32 v91, v20, v21 offset1:1
	s_waitcnt vmcnt(2)
	ds_write2_b32 v92, v22, v23 offset1:1
	ds_write2_b32 v93, v24, v25 offset1:1
	s_waitcnt vmcnt(1)
	ds_write2_b32 v94, v26, v27 offset1:1
	ds_write2_b32 v95, v28, v29 offset1:1
	s_waitcnt vmcnt(0)
	ds_write2_b32 v96, v30, v31 offset1:1
	ds_write2_b32 v97, v32, v33 offset1:1
	s_waitcnt lgkmcnt(0)
	v_or_b32_e32 v10, s14, v1
	ds_read2_b32 v[2:3], v80 offset1:33
	v_mul_u32_u24_e32 v10, 0xb00, v10
	s_waitcnt lgkmcnt(0)
	v_cvt_pk_bf16_f32 v2, v2, v3
	ds_read2_b32 v[4:5], v80 offset0:66 offset1:99
	v_lshl_add_u64 v[8:9], s[4:5], 1, v[38:39]
	v_lshlrev_b32_e32 v36, 1, v10
	s_waitcnt lgkmcnt(0)
	v_cvt_pk_bf16_f32 v3, v4, v5
	ds_read2_b32 v[4:5], v80 offset0:132 offset1:165
	v_lshl_add_u64 v[10:11], v[8:9], 0, v[36:37]
	s_waitcnt lgkmcnt(0)
	v_cvt_pk_bf16_f32 v4, v4, v5
	ds_read2_b32 v[6:7], v80 offset0:198 offset1:231
	s_waitcnt lgkmcnt(0)
	v_cvt_pk_bf16_f32 v5, v6, v7
	global_store_dwordx4 v[10:11], v[2:5], off
	v_or_b32_e32 v10, s14, v77
	v_mul_u32_u24_e32 v10, 0xb00, v10
	ds_read2_b32 v[6:7], v80 offset0:8 offset1:41
	s_waitcnt lgkmcnt(0)
	v_cvt_pk_bf16_f32 v2, v6, v7
	ds_read2_b32 v[4:5], v80 offset0:74 offset1:107
	v_lshlrev_b32_e32 v36, 1, v10
	s_waitcnt lgkmcnt(0)
	v_cvt_pk_bf16_f32 v3, v4, v5
	ds_read2_b32 v[4:5], v80 offset0:140 offset1:173
	v_lshl_add_u64 v[10:11], v[8:9], 0, v[36:37]
	s_waitcnt lgkmcnt(0)
	v_cvt_pk_bf16_f32 v4, v4, v5
	ds_read2_b32 v[6:7], v80 offset0:206 offset1:239
	s_waitcnt lgkmcnt(0)
	v_cvt_pk_bf16_f32 v5, v6, v7
	global_store_dwordx4 v[10:11], v[2:5], off
	v_or_b32_e32 v10, s14, v78
	ds_read2_b32 v[6:7], v80 offset0:16 offset1:49
	s_waitcnt lgkmcnt(0)
	v_cvt_pk_bf16_f32 v2, v6, v7
	ds_read2_b32 v[4:5], v80 offset0:82 offset1:115
	v_mul_u32_u24_e32 v10, 0xb00, v10
	s_waitcnt lgkmcnt(0)
	v_cvt_pk_bf16_f32 v3, v4, v5
	ds_read2_b32 v[4:5], v80 offset0:148 offset1:181
	v_lshlrev_b32_e32 v36, 1, v10
	s_waitcnt lgkmcnt(0)
	v_cvt_pk_bf16_f32 v4, v4, v5
	ds_read2_b32 v[6:7], v80 offset0:214 offset1:247
	s_waitcnt lgkmcnt(0)
	v_cvt_pk_bf16_f32 v5, v6, v7
	v_lshl_add_u64 v[10:11], v[8:9], 0, v[36:37]
	ds_read2_b32 v[6:7], v80 offset0:24 offset1:57
	global_store_dwordx4 v[10:11], v[2:5], off
	s_waitcnt lgkmcnt(0)
	s_nop 0
	v_cvt_pk_bf16_f32 v2, v6, v7
	ds_read2_b32 v[4:5], v80 offset0:90 offset1:123
	s_waitcnt lgkmcnt(0)
	v_cvt_pk_bf16_f32 v3, v4, v5
	ds_read2_b32 v[4:5], v80 offset0:156 offset1:189
	s_waitcnt lgkmcnt(0)
	v_cvt_pk_bf16_f32 v4, v4, v5
	v_or_b32_e32 v5, s14, v79
	v_mul_u32_u24_e32 v5, 0xb00, v5
	ds_read2_b32 v[6:7], v80 offset0:222 offset1:255
	v_lshlrev_b32_e32 v36, 1, v5
	s_waitcnt lgkmcnt(0)
	v_cvt_pk_bf16_f32 v5, v6, v7
	v_lshl_add_u64 v[6:7], v[8:9], 0, v[36:37]
	global_store_dwordx4 v[6:7], v[2:5], off
	s_waitcnt lgkmcnt(0)

.LBB0_24:
	s_andn2_b64 vcc, exec, s[4:5]
	s_cbranch_vccnz .LBB0_34
	s_add_i32 s4, s50, 0xde80
	s_and_b32 s5, s4, 0xffff
	s_mul_i32 s5, s5, 0xba2f
	s_lshr_b32 s5, s5, 23
	s_mul_i32 s14, s5, 0xb0
	s_sub_i32 s15, s4, s14
	s_lshl_b32 s14, s5, 6
	s_lshl_b32 s4, s15, 7
	v_or_b32_e32 v73, s14, v1
	s_and_b32 s26, s4, 0x3ff80
	v_lshl_add_u64 v[2:3], v[56:57], 0, s[26:27]
	v_or_b32_e32 v6, 8, v73
	v_mad_u64_u32 v[4:5], s[4:5], v73, s47, v[2:3]
	v_mad_u64_u32 v[6:7], s[4:5], v6, s47, v[2:3]
	global_load_dwordx4 v[30:33], v[4:5], off nt
	global_load_dwordx4 v[26:29], v[6:7], off nt
	v_or_b32_e32 v4, 16, v73
	v_or_b32_e32 v6, 24, v73
	v_mad_u64_u32 v[4:5], s[4:5], v4, s47, v[2:3]
	v_mad_u64_u32 v[6:7], s[4:5], v6, s47, v[2:3]
	global_load_dwordx4 v[22:25], v[4:5], off nt
	global_load_dwordx4 v[18:21], v[6:7], off nt
	v_or_b32_e32 v4, 32, v73
	v_or_b32_e32 v6, 40, v73
	v_mad_u64_u32 v[4:5], s[4:5], v4, s47, v[2:3]
	v_mad_u64_u32 v[6:7], s[4:5], v6, s47, v[2:3]
	global_load_dwordx4 v[14:17], v[4:5], off nt
	global_load_dwordx4 v[10:13], v[6:7], off nt
	v_or_b32_e32 v4, 48, v73
	v_or_b32_e32 v6, 56, v73
	v_mad_u64_u32 v[4:5], s[4:5], v4, s47, v[2:3]
	v_mad_u64_u32 v[2:3], s[4:5], v6, s47, v[2:3]
	global_load_dwordx4 v[6:9], v[4:5], off nt
	s_nop 0
	global_load_dwordx4 v[2:5], v[2:3], off nt
	v_cndmask_b32_e64 v75, 0, 1, s[28:29]
	v_mov_b32_e32 v36, 1.0
	v_cmp_ne_u32_e64 s[4:5], 1, v75
	s_andn2_b64 vcc, exec, s[28:29]
	v_lshlrev_b32_e32 v73, 2, v73
	v_mov_b32_e32 v76, 1.0
	s_cbranch_vccnz .LBB0_27
	global_load_dword v90, v73, s[6:7]
	global_load_dword v76, v73, s[6:7] offset:32
	s_waitcnt vmcnt(1)
	v_pk_mul_f32 v[30:31], v[30:31], v[90:91] op_sel_hi:[1,0]
	v_pk_mul_f32 v[32:33], v[32:33], v[90:91] op_sel_hi:[1,0]

.LBB0_35:
	s_andn2_b64 vcc, exec, s[4:5]
	s_cbranch_vccnz .LBB0_37
	s_and_b32 s4, s35, 0x7fc0
	s_addk_i32 s4, 0xc100
	s_and_b32 s14, s9, 0x3e0
	v_or_b32_e32 v36, s4, v1
	s_lshl_b32 s26, s14, 2
	v_or_b32_e32 v4, 8, v36
	v_mov_b32_e32 v5, v37
	v_or_b32_e32 v10, 16, v36
	v_mov_b32_e32 v11, v37
	v_or_b32_e32 v12, 24, v36
	v_mov_b32_e32 v13, v37
	v_or_b32_e32 v18, 32, v36
	v_mov_b32_e32 v19, v37
	v_or_b32_e32 v20, 40, v36
	v_mov_b32_e32 v21, v37
	v_lshl_add_u64 v[30:31], v[58:59], 0, s[26:27]
	v_lshlrev_b64 v[2:3], 12, v[36:37]
	v_lshlrev_b64 v[4:5], 12, v[4:5]
	v_lshlrev_b64 v[10:11], 12, v[10:11]
	v_lshlrev_b64 v[12:13], 12, v[12:13]
	v_lshlrev_b64 v[18:19], 12, v[18:19]
	v_lshlrev_b64 v[20:21], 12, v[20:21]
	v_lshl_add_u64 v[2:3], v[30:31], 0, v[2:3]
	v_lshl_add_u64 v[6:7], v[30:31], 0, v[4:5]
	v_lshl_add_u64 v[10:11], v[30:31], 0, v[10:11]
	v_lshl_add_u64 v[14:15], v[30:31], 0, v[12:13]
	v_lshl_add_u64 v[18:19], v[30:31], 0, v[18:19]
	v_lshl_add_u64 v[22:23], v[30:31], 0, v[20:21]
	global_load_dwordx4 v[2:5], v[2:3], off nt
	s_nop 0
	global_load_dwordx4 v[6:9], v[6:7], off nt
	s_nop 0
	global_load_dwordx4 v[10:13], v[10:11], off nt
	s_nop 0
	global_load_dwordx4 v[14:17], v[14:15], off nt
	s_nop 0
	global_load_dwordx4 v[18:21], v[18:19], off nt
	s_nop 0
	global_load_dwordx4 v[22:25], v[22:23], off nt
	v_or_b32_e32 v26, 48, v36
	v_mov_b32_e32 v27, v37
	v_lshlrev_b64 v[26:27], 12, v[26:27]
	v_lshl_add_u64 v[26:27], v[30:31], 0, v[26:27]
	v_or_b32_e32 v36, 56, v36
	global_load_dwordx4 v[26:29], v[26:27], off nt
	v_lshlrev_b64 v[32:33], 12, v[36:37]
	v_lshl_add_u64 v[30:31], v[30:31], 0, v[32:33]
	global_load_dwordx4 v[30:33], v[30:31], off nt
	v_add_u32_e32 v36, 0x428, v87
	v_add_u32_e32 v73, 0x840, v87
	v_add_u32_e32 v75, 0x848, v87
	v_add_u32_e32 v76, 0xc60, v87
	v_add_u32_e32 v89, 0xc68, v87
	v_add_u32_e32 v90, 0x1080, v87
	v_add_u32_e32 v91, 0x1088, v87
	v_add_u32_e32 v92, 0x14a0, v87
	v_add_u32_e32 v93, 0x14a8, v87
	v_add_u32_e32 v94, 0x18c0, v87
	v_add_u32_e32 v95, 0x18c8, v87
	v_add_u32_e32 v96, 0x1ce0, v87
	v_add_u32_e32 v97, 0x1ce8, v87
	s_mov_b32 s5, s27
	s_waitcnt vmcnt(7)
	ds_write2_b32 v87, v2, v3 offset1:1
	ds_write2_b32 v87, v4, v5 offset0:2 offset1:3
	s_waitcnt vmcnt(6)
	ds_write2_b32 v88, v6, v7 offset1:1
	ds_write2_b32 v36, v8, v9 offset1:1
	s_waitcnt vmcnt(5)
	ds_write2_b32 v73, v10, v11 offset1:1
	ds_write2_b32 v75, v12, v13 offset1:1
	s_waitcnt vmcnt(4)
	ds_write2_b32 v76, v14, v15 offset1:1
	ds_write2_b32 v89, v16, v17 offset1:1
	s_waitcnt vmcnt(3)
	ds_write2_b32 v90, v18, v19 offset1:1
	ds_write2_b32 v91, v20, v21 offset1:1
	s_waitcnt vmcnt(2)
	ds_write2_b32 v92, v22, v23 offset1:1
	ds_write2_b32 v93, v24, v25 offset1:1
	s_waitcnt vmcnt(1)
	ds_write2_b32 v94, v26, v27 offset1:1
	ds_write2_b32 v95, v28, v29 offset1:1
	s_waitcnt vmcnt(0)
	ds_write2_b32 v96, v30, v31 offset1:1
	ds_write2_b32 v97, v32, v33 offset1:1
	s_waitcnt lgkmcnt(0)
	ds_read2_b32 v[2:3], v80 offset1:33
	s_waitcnt lgkmcnt(0)
	v_cvt_pk_bf16_f32 v2, v2, v3
	ds_read2_b32 v[4:5], v80 offset0:66 offset1:99
	v_or_b32_e32 v10, s14, v1
	s_waitcnt lgkmcnt(0)
	v_cvt_pk_bf16_f32 v3, v4, v5
	ds_read2_b32 v[4:5], v80 offset0:132 offset1:165
	v_lshl_add_u64 v[8:9], s[4:5], 1, v[42:43]
	v_lshlrev_b32_e32 v36, 11, v10
	s_waitcnt lgkmcnt(0)
	v_cvt_pk_bf16_f32 v4, v4, v5
	ds_read2_b32 v[6:7], v80 offset0:198 offset1:231
	s_waitcnt lgkmcnt(0)
	v_cvt_pk_bf16_f32 v5, v6, v7
	v_lshl_add_u64 v[10:11], v[8:9], 0, v[36:37]
	ds_read2_b32 v[6:7], v80 offset0:8 offset1:41
	global_store_dwordx4 v[10:11], v[2:5], off
	v_or_b32_e32 v10, s14, v77
	v_lshlrev_b32_e32 v36, 11, v10
	s_waitcnt lgkmcnt(0)
	v_cvt_pk_bf16_f32 v2, v6, v7
	ds_read2_b32 v[4:5], v80 offset0:74 offset1:107
	s_waitcnt lgkmcnt(0)
	v_cvt_pk_bf16_f32 v3, v4, v5
	ds_read2_b32 v[4:5], v80 offset0:140 offset1:173
	s_waitcnt lgkmcnt(0)
	v_cvt_pk_bf16_f32 v4, v4, v5
	ds_read2_b32 v[6:7], v80 offset0:206 offset1:239
	s_waitcnt lgkmcnt(0)
	v_cvt_pk_bf16_f32 v5, v6, v7
	v_lshl_add_u64 v[10:11], v[8:9], 0, v[36:37]
	ds_read2_b32 v[6:7], v80 offset0:16 offset1:49
	global_store_dwordx4 v[10:11], v[2:5], off
	v_or_b32_e32 v10, s14, v78
	v_lshlrev_b32_e32 v36, 11, v10
	s_waitcnt lgkmcnt(0)
	v_cvt_pk_bf16_f32 v2, v6, v7
	ds_read2_b32 v[4:5], v80 offset0:82 offset1:115
	s_waitcnt lgkmcnt(0)
	v_cvt_pk_bf16_f32 v3, v4, v5
	ds_read2_b32 v[4:5], v80 offset0:148 offset1:181
	s_waitcnt lgkmcnt(0)
	v_cvt_pk_bf16_f32 v4, v4, v5
	ds_read2_b32 v[6:7], v80 offset0:214 offset1:247
	s_waitcnt lgkmcnt(0)
	v_cvt_pk_bf16_f32 v5, v6, v7
	v_lshl_add_u64 v[10:11], v[8:9], 0, v[36:37]
	ds_read2_b32 v[6:7], v80 offset0:24 offset1:57
	global_store_dwordx4 v[10:11], v[2:5], off
	s_waitcnt lgkmcnt(0)
	s_nop 0
	v_cvt_pk_bf16_f32 v2, v6, v7
	ds_read2_b32 v[4:5], v80 offset0:90 offset1:123
	s_waitcnt lgkmcnt(0)
	v_cvt_pk_bf16_f32 v3, v4, v5
	ds_read2_b32 v[4:5], v80 offset0:156 offset1:189
	s_waitcnt lgkmcnt(0)
	v_cvt_pk_bf16_f32 v4, v4, v5
	v_or_b32_e32 v5, s14, v79
	ds_read2_b32 v[6:7], v80 offset0:222 offset1:255
	v_lshlrev_b32_e32 v36, 11, v5
	s_waitcnt lgkmcnt(0)
	v_cvt_pk_bf16_f32 v5, v6, v7
	v_lshl_add_u64 v[6:7], v[8:9], 0, v[36:37]
	global_store_dwordx4 v[6:7], v[2:5], off
	s_waitcnt lgkmcnt(0)

.LBB0_38:
	s_andn2_b64 vcc, exec, s[4:5]
	s_cbranch_vccnz .LBB0_56
	s_add_i32 s4, s50, 0xe680
	s_and_b32 s5, s4, 0xffff
	s_mul_i32 s5, s5, 0xaaab
	s_lshr_b32 s15, s5, 16
	s_lshr_b32 s5, s5, 22
	s_mulk_i32 s5, 0x60
	s_sub_i32 s14, s4, s5
	s_and_b32 s51, s15, 0xffc0
	s_lshl_b32 s4, s14, 7
	v_or_b32_e32 v73, s51, v1
	s_and_b32 s26, s4, 0x3ff80
	v_lshl_add_u64 v[2:3], v[60:61], 0, s[26:27]
	v_or_b32_e32 v6, 8, v73
	v_mad_u64_u32 v[4:5], s[4:5], v73, s41, v[2:3]
	v_mad_u64_u32 v[6:7], s[4:5], v6, s41, v[2:3]
	global_load_dwordx4 v[30:33], v[4:5], off nt
	global_load_dwordx4 v[26:29], v[6:7], off nt
	v_or_b32_e32 v4, 16, v73
	v_or_b32_e32 v6, 24, v73
	v_mad_u64_u32 v[4:5], s[4:5], v4, s41, v[2:3]
	v_mad_u64_u32 v[6:7], s[4:5], v6, s41, v[2:3]
	global_load_dwordx4 v[22:25], v[4:5], off nt
	global_load_dwordx4 v[18:21], v[6:7], off nt
	v_or_b32_e32 v4, 32, v73
	v_or_b32_e32 v6, 40, v73
	v_mad_u64_u32 v[4:5], s[4:5], v4, s41, v[2:3]
	v_mad_u64_u32 v[6:7], s[4:5], v6, s41, v[2:3]
	global_load_dwordx4 v[14:17], v[4:5], off nt
	global_load_dwordx4 v[10:13], v[6:7], off nt
	v_or_b32_e32 v4, 48, v73
	v_or_b32_e32 v6, 56, v73
	v_mad_u64_u32 v[4:5], s[4:5], v4, s41, v[2:3]
	v_mad_u64_u32 v[2:3], s[4:5], v6, s41, v[2:3]
	global_load_dwordx4 v[6:9], v[4:5], off nt
	s_nop 0
	global_load_dwordx4 v[2:5], v[2:3], off nt
	v_cndmask_b32_e64 v75, 0, 1, s[18:19]
	v_mov_b32_e32 v36, 1.0
	v_cmp_ne_u32_e64 s[4:5], 1, v75
	s_andn2_b64 vcc, exec, s[18:19]
	v_lshlrev_b32_e32 v73, 2, v73
	v_mov_b32_e32 v76, 1.0
	s_cbranch_vccnz .LBB0_41
	global_load_dword v90, v73, s[16:17]
	global_load_dword v76, v73, s[16:17] offset:32
	s_waitcnt vmcnt(1)
	v_pk_mul_f32 v[30:31], v[30:31], v[90:91] op_sel_hi:[1,0]
	v_pk_mul_f32 v[32:33], v[32:33], v[90:91] op_sel_hi:[1,0]

.LBB0_57:
	s_andn2_b64 vcc, exec, s[4:5]
	s_cbranch_vccnz .LBB0_83
	s_add_i32 s4, s50, 0xe980
	s_and_b32 s5, s4, 0xffff
	s_mul_i32 s5, s5, 0xaaab
	s_lshr_b32 s5, s5, 21
	s_mul_i32 s14, s5, 48
	s_sub_i32 s4, s4, s14
	s_and_b32 s14, s4, 0xffff
	s_lshl_b32 s51, s5, 6
	v_or_b32_e32 v73, s51, v1
	s_lshl_b32 s26, s14, 7
	v_lshl_add_u64 v[2:3], v[62:63], 0, s[26:27]
	v_or_b32_e32 v6, 8, v73
	v_mad_u64_u32 v[4:5], s[4:5], v73, s49, v[2:3]
	v_mad_u64_u32 v[6:7], s[4:5], v6, s49, v[2:3]
	global_load_dwordx4 v[30:33], v[4:5], off nt
	global_load_dwordx4 v[26:29], v[6:7], off nt
	v_or_b32_e32 v4, 16, v73
	v_or_b32_e32 v6, 24, v73
	v_mad_u64_u32 v[4:5], s[4:5], v4, s49, v[2:3]
	v_mad_u64_u32 v[6:7], s[4:5], v6, s49, v[2:3]
	global_load_dwordx4 v[22:25], v[4:5], off nt
	global_load_dwordx4 v[18:21], v[6:7], off nt
	v_or_b32_e32 v4, 32, v73
	v_or_b32_e32 v6, 40, v73
	v_mad_u64_u32 v[4:5], s[4:5], v4, s49, v[2:3]
	v_mad_u64_u32 v[6:7], s[4:5], v6, s49, v[2:3]
	global_load_dwordx4 v[14:17], v[4:5], off nt
	global_load_dwordx4 v[10:13], v[6:7], off nt
	v_or_b32_e32 v4, 48, v73
	v_or_b32_e32 v6, 56, v73
	v_mad_u64_u32 v[4:5], s[4:5], v4, s49, v[2:3]
	v_mad_u64_u32 v[2:3], s[4:5], v6, s49, v[2:3]
	global_load_dwordx4 v[6:9], v[4:5], off nt
	s_nop 0
	global_load_dwordx4 v[2:5], v[2:3], off nt
	v_cndmask_b32_e64 v75, 0, 1, s[22:23]
	v_mov_b32_e32 v36, 1.0
	v_cmp_ne_u32_e64 s[4:5], 1, v75
	s_andn2_b64 vcc, exec, s[22:23]
	v_lshlrev_b32_e32 v73, 2, v73
	v_mov_b32_e32 v76, 1.0
	s_cbranch_vccnz .LBB0_60
	global_load_dword v90, v73, s[20:21]
	global_load_dword v76, v73, s[20:21] offset:32
	s_waitcnt vmcnt(1)
	v_pk_mul_f32 v[30:31], v[30:31], v[90:91] op_sel_hi:[1,0]
	v_pk_mul_f32 v[32:33], v[32:33], v[90:91] op_sel_hi:[1,0]

.LBB0_84:
	s_andn2_b64 vcc, exec, s[4:5]
	s_cbranch_vccnz .LBB0_86
	s_and_b32 s4, s35, 0x3fc0
	s_addk_i32 s4, 0xde00
	s_and_b32 s14, s9, 0x3e0
	v_or_b32_e32 v36, s4, v1
	s_lshl_b32 s26, s14, 2
	v_or_b32_e32 v4, 8, v36
	v_mov_b32_e32 v5, v37
	v_or_b32_e32 v10, 16, v36
	v_mov_b32_e32 v11, v37
	v_or_b32_e32 v12, 24, v36
	v_mov_b32_e32 v13, v37
	v_or_b32_e32 v18, 32, v36
	v_mov_b32_e32 v19, v37
	v_or_b32_e32 v20, 40, v36
	v_mov_b32_e32 v21, v37
	v_lshl_add_u64 v[30:31], v[64:65], 0, s[26:27]
	v_lshlrev_b64 v[2:3], 12, v[36:37]
	v_lshlrev_b64 v[4:5], 12, v[4:5]
	v_lshlrev_b64 v[10:11], 12, v[10:11]
	v_lshlrev_b64 v[12:13], 12, v[12:13]
	v_lshlrev_b64 v[18:19], 12, v[18:19]
	v_lshlrev_b64 v[20:21], 12, v[20:21]
	v_lshl_add_u64 v[2:3], v[30:31], 0, v[2:3]
	v_lshl_add_u64 v[6:7], v[30:31], 0, v[4:5]
	v_lshl_add_u64 v[10:11], v[30:31], 0, v[10:11]
	v_lshl_add_u64 v[14:15], v[30:31], 0, v[12:13]
	v_lshl_add_u64 v[18:19], v[30:31], 0, v[18:19]
	v_lshl_add_u64 v[22:23], v[30:31], 0, v[20:21]
	global_load_dwordx4 v[2:5], v[2:3], off nt
	s_nop 0
	global_load_dwordx4 v[6:9], v[6:7], off nt
	s_nop 0
	global_load_dwordx4 v[10:13], v[10:11], off nt
	s_nop 0
	global_load_dwordx4 v[14:17], v[14:15], off nt
	s_nop 0
	global_load_dwordx4 v[18:21], v[18:19], off nt
	s_nop 0
	global_load_dwordx4 v[22:25], v[22:23], off nt
	v_or_b32_e32 v26, 48, v36
	v_mov_b32_e32 v27, v37
	v_lshlrev_b64 v[26:27], 12, v[26:27]
	v_lshl_add_u64 v[26:27], v[30:31], 0, v[26:27]
	v_or_b32_e32 v36, 56, v36
	global_load_dwordx4 v[26:29], v[26:27], off nt
	v_lshlrev_b64 v[32:33], 12, v[36:37]
	v_lshl_add_u64 v[30:31], v[30:31], 0, v[32:33]
	global_load_dwordx4 v[30:33], v[30:31], off nt
	v_add_u32_e32 v36, 0x428, v87
	v_add_u32_e32 v73, 0x840, v87
	v_add_u32_e32 v75, 0x848, v87
	v_add_u32_e32 v76, 0xc60, v87
	v_add_u32_e32 v89, 0xc68, v87
	v_add_u32_e32 v90, 0x1080, v87
	v_add_u32_e32 v91, 0x1088, v87
	v_add_u32_e32 v92, 0x14a0, v87
	v_add_u32_e32 v93, 0x14a8, v87
	v_add_u32_e32 v94, 0x18c0, v87
	v_add_u32_e32 v95, 0x18c8, v87
	v_add_u32_e32 v96, 0x1ce0, v87
	v_add_u32_e32 v97, 0x1ce8, v87
	s_mov_b32 s5, s27
	s_waitcnt vmcnt(7)
	ds_write2_b32 v87, v2, v3 offset1:1
	ds_write2_b32 v87, v4, v5 offset0:2 offset1:3
	s_waitcnt vmcnt(6)
	ds_write2_b32 v88, v6, v7 offset1:1
	ds_write2_b32 v36, v8, v9 offset1:1
	s_waitcnt vmcnt(5)
	ds_write2_b32 v73, v10, v11 offset1:1
	ds_write2_b32 v75, v12, v13 offset1:1
	s_waitcnt vmcnt(4)
	ds_write2_b32 v76, v14, v15 offset1:1
	ds_write2_b32 v89, v16, v17 offset1:1
	s_waitcnt vmcnt(3)
	ds_write2_b32 v90, v18, v19 offset1:1
	ds_write2_b32 v91, v20, v21 offset1:1
	s_waitcnt vmcnt(2)
	ds_write2_b32 v92, v22, v23 offset1:1
	ds_write2_b32 v93, v24, v25 offset1:1
	s_waitcnt vmcnt(1)
	ds_write2_b32 v94, v26, v27 offset1:1
	ds_write2_b32 v95, v28, v29 offset1:1
	s_waitcnt vmcnt(0)
	ds_write2_b32 v96, v30, v31 offset1:1
	ds_write2_b32 v97, v32, v33 offset1:1
	s_waitcnt lgkmcnt(0)
	v_or_b32_e32 v10, s14, v1
	ds_read2_b32 v[2:3], v80 offset1:33
	v_mul_u32_u24_e32 v10, 0xb00, v10
	s_waitcnt lgkmcnt(0)
	v_cvt_pk_bf16_f32 v2, v2, v3
	ds_read2_b32 v[4:5], v80 offset0:66 offset1:99
	v_lshl_add_u64 v[8:9], s[4:5], 1, v[46:47]
	v_lshlrev_b32_e32 v36, 1, v10
	s_waitcnt lgkmcnt(0)
	v_cvt_pk_bf16_f32 v3, v4, v5
	ds_read2_b32 v[4:5], v80 offset0:132 offset1:165
	v_lshl_add_u64 v[10:11], v[8:9], 0, v[36:37]
	s_waitcnt lgkmcnt(0)
	v_cvt_pk_bf16_f32 v4, v4, v5
	ds_read2_b32 v[6:7], v80 offset0:198 offset1:231
	s_waitcnt lgkmcnt(0)
	v_cvt_pk_bf16_f32 v5, v6, v7
	global_store_dwordx4 v[10:11], v[2:5], off
	v_or_b32_e32 v10, s14, v77
	v_mul_u32_u24_e32 v10, 0xb00, v10
	ds_read2_b32 v[6:7], v80 offset0:8 offset1:41
	s_waitcnt lgkmcnt(0)
	v_cvt_pk_bf16_f32 v2, v6, v7
	ds_read2_b32 v[4:5], v80 offset0:74 offset1:107
	v_lshlrev_b32_e32 v36, 1, v10
	s_waitcnt lgkmcnt(0)
	v_cvt_pk_bf16_f32 v3, v4, v5
	ds_read2_b32 v[4:5], v80 offset0:140 offset1:173
	v_lshl_add_u64 v[10:11], v[8:9], 0, v[36:37]
	s_waitcnt lgkmcnt(0)
	v_cvt_pk_bf16_f32 v4, v4, v5
	ds_read2_b32 v[6:7], v80 offset0:206 offset1:239
	s_waitcnt lgkmcnt(0)
	v_cvt_pk_bf16_f32 v5, v6, v7
	global_store_dwordx4 v[10:11], v[2:5], off
	v_or_b32_e32 v10, s14, v78
	ds_read2_b32 v[6:7], v80 offset0:16 offset1:49
	s_waitcnt lgkmcnt(0)
	v_cvt_pk_bf16_f32 v2, v6, v7
	ds_read2_b32 v[4:5], v80 offset0:82 offset1:115
	v_mul_u32_u24_e32 v10, 0xb00, v10
	s_waitcnt lgkmcnt(0)
	v_cvt_pk_bf16_f32 v3, v4, v5
	ds_read2_b32 v[4:5], v80 offset0:148 offset1:181
	v_lshlrev_b32_e32 v36, 1, v10
	s_waitcnt lgkmcnt(0)
	v_cvt_pk_bf16_f32 v4, v4, v5
	ds_read2_b32 v[6:7], v80 offset0:214 offset1:247
	s_waitcnt lgkmcnt(0)
	v_cvt_pk_bf16_f32 v5, v6, v7
	v_lshl_add_u64 v[10:11], v[8:9], 0, v[36:37]
	ds_read2_b32 v[6:7], v80 offset0:24 offset1:57
	global_store_dwordx4 v[10:11], v[2:5], off
	s_waitcnt lgkmcnt(0)
	s_nop 0
	v_cvt_pk_bf16_f32 v2, v6, v7
	ds_read2_b32 v[4:5], v80 offset0:90 offset1:123
	s_waitcnt lgkmcnt(0)
	v_cvt_pk_bf16_f32 v3, v4, v5
	ds_read2_b32 v[4:5], v80 offset0:156 offset1:189
	s_waitcnt lgkmcnt(0)
	v_cvt_pk_bf16_f32 v4, v4, v5
	v_or_b32_e32 v5, s14, v79
	v_mul_u32_u24_e32 v5, 0xb00, v5
	ds_read2_b32 v[6:7], v80 offset0:222 offset1:255
	v_lshlrev_b32_e32 v36, 1, v5
	s_waitcnt lgkmcnt(0)
	v_cvt_pk_bf16_f32 v5, v6, v7
	v_lshl_add_u64 v[6:7], v[8:9], 0, v[36:37]
	global_store_dwordx4 v[6:7], v[2:5], off
	s_waitcnt lgkmcnt(0)

.LBB0_87:
	s_andn2_b64 vcc, exec, s[4:5]
	s_cbranch_vccnz .LBB0_97
	s_add_i32 s4, s50, 0xfa00
	s_and_b32 s5, s4, 0xffff
	s_mul_i32 s5, s5, 0xba2f
	s_lshr_b32 s5, s5, 23
	s_mul_i32 s14, s5, 0xb0
	s_sub_i32 s15, s4, s14
	s_lshl_b32 s14, s5, 6
	s_lshl_b32 s4, s15, 7
	v_or_b32_e32 v73, s14, v1
	s_and_b32 s26, s4, 0x3ff80
	v_lshl_add_u64 v[2:3], v[66:67], 0, s[26:27]
	v_or_b32_e32 v6, 8, v73
	v_mad_u64_u32 v[4:5], s[4:5], v73, s47, v[2:3]
	v_mad_u64_u32 v[6:7], s[4:5], v6, s47, v[2:3]
	global_load_dwordx4 v[30:33], v[4:5], off nt
	global_load_dwordx4 v[26:29], v[6:7], off nt
	v_or_b32_e32 v4, 16, v73
	v_or_b32_e32 v6, 24, v73
	v_mad_u64_u32 v[4:5], s[4:5], v4, s47, v[2:3]
	v_mad_u64_u32 v[6:7], s[4:5], v6, s47, v[2:3]
	global_load_dwordx4 v[22:25], v[4:5], off nt
	global_load_dwordx4 v[18:21], v[6:7], off nt
	v_or_b32_e32 v4, 32, v73
	v_or_b32_e32 v6, 40, v73
	v_mad_u64_u32 v[4:5], s[4:5], v4, s47, v[2:3]
	v_mad_u64_u32 v[6:7], s[4:5], v6, s47, v[2:3]
	global_load_dwordx4 v[14:17], v[4:5], off nt
	global_load_dwordx4 v[10:13], v[6:7], off nt
	v_or_b32_e32 v4, 48, v73
	v_or_b32_e32 v6, 56, v73
	v_mad_u64_u32 v[4:5], s[4:5], v4, s47, v[2:3]
	v_mad_u64_u32 v[2:3], s[4:5], v6, s47, v[2:3]
	global_load_dwordx4 v[6:9], v[4:5], off nt
	s_nop 0
	global_load_dwordx4 v[2:5], v[2:3], off nt
	v_cndmask_b32_e64 v75, 0, 1, s[12:13]
	v_mov_b32_e32 v36, 1.0
	v_cmp_ne_u32_e64 s[4:5], 1, v75
	s_andn2_b64 vcc, exec, s[12:13]
	v_lshlrev_b32_e32 v73, 2, v73
	v_mov_b32_e32 v76, 1.0
	s_cbranch_vccnz .LBB0_90
	global_load_dword v90, v73, s[10:11]
	global_load_dword v76, v73, s[10:11] offset:32
	s_waitcnt vmcnt(1)
	v_pk_mul_f32 v[30:31], v[30:31], v[90:91] op_sel_hi:[1,0]
	v_pk_mul_f32 v[32:33], v[32:33], v[90:91] op_sel_hi:[1,0]

.LBB0_98:
	s_andn2_b64 vcc, exec, s[4:5]
	s_cbranch_vccnz .LBB0_100
	s_and_b32 s4, s35, 0xfc0
	s_addk_i32 s4, 0xf800
	s_and_b32 s14, s9, 0x3e0
	v_or_b32_e32 v36, s4, v1
	s_lshl_b32 s26, s14, 2
	v_or_b32_e32 v4, 8, v36
	v_mov_b32_e32 v5, v37
	v_or_b32_e32 v10, 16, v36
	v_mov_b32_e32 v11, v37
	v_or_b32_e32 v12, 24, v36
	v_mov_b32_e32 v13, v37
	v_or_b32_e32 v18, 32, v36
	v_mov_b32_e32 v19, v37
	v_or_b32_e32 v20, 40, v36
	v_mov_b32_e32 v21, v37
	v_lshl_add_u64 v[30:31], v[68:69], 0, s[26:27]
	v_lshlrev_b64 v[2:3], 12, v[36:37]
	v_lshlrev_b64 v[4:5], 12, v[4:5]
	v_lshlrev_b64 v[10:11], 12, v[10:11]
	v_lshlrev_b64 v[12:13], 12, v[12:13]
	v_lshlrev_b64 v[18:19], 12, v[18:19]
	v_lshlrev_b64 v[20:21], 12, v[20:21]
	v_lshl_add_u64 v[2:3], v[30:31], 0, v[2:3]
	v_lshl_add_u64 v[6:7], v[30:31], 0, v[4:5]
	v_lshl_add_u64 v[10:11], v[30:31], 0, v[10:11]
	v_lshl_add_u64 v[14:15], v[30:31], 0, v[12:13]
	v_lshl_add_u64 v[18:19], v[30:31], 0, v[18:19]
	v_lshl_add_u64 v[22:23], v[30:31], 0, v[20:21]
	global_load_dwordx4 v[2:5], v[2:3], off nt
	s_nop 0
	global_load_dwordx4 v[6:9], v[6:7], off nt
	s_nop 0
	global_load_dwordx4 v[10:13], v[10:11], off nt
	s_nop 0
	global_load_dwordx4 v[14:17], v[14:15], off nt
	s_nop 0
	global_load_dwordx4 v[18:21], v[18:19], off nt
	s_nop 0
	global_load_dwordx4 v[22:25], v[22:23], off nt
	v_or_b32_e32 v26, 48, v36
	v_mov_b32_e32 v27, v37
	v_lshlrev_b64 v[26:27], 12, v[26:27]
	v_lshl_add_u64 v[26:27], v[30:31], 0, v[26:27]
	v_or_b32_e32 v36, 56, v36
	global_load_dwordx4 v[26:29], v[26:27], off nt
	v_lshlrev_b64 v[32:33], 12, v[36:37]
	v_lshl_add_u64 v[30:31], v[30:31], 0, v[32:33]
	global_load_dwordx4 v[30:33], v[30:31], off nt
	v_add_u32_e32 v36, 0x428, v87
	v_add_u32_e32 v73, 0x840, v87
	v_add_u32_e32 v75, 0x848, v87
	v_add_u32_e32 v76, 0xc60, v87
	v_add_u32_e32 v89, 0xc68, v87
	v_add_u32_e32 v90, 0x1080, v87
	v_add_u32_e32 v91, 0x1088, v87
	v_add_u32_e32 v92, 0x14a0, v87
	v_add_u32_e32 v93, 0x14a8, v87
	v_add_u32_e32 v94, 0x18c0, v87
	v_add_u32_e32 v95, 0x18c8, v87
	v_add_u32_e32 v96, 0x1ce0, v87
	v_add_u32_e32 v97, 0x1ce8, v87
	s_mov_b32 s5, s27
	s_waitcnt vmcnt(7)
	ds_write2_b32 v87, v2, v3 offset1:1
	ds_write2_b32 v87, v4, v5 offset0:2 offset1:3
	s_waitcnt vmcnt(6)
	ds_write2_b32 v88, v6, v7 offset1:1
	ds_write2_b32 v36, v8, v9 offset1:1
	s_waitcnt vmcnt(5)
	ds_write2_b32 v73, v10, v11 offset1:1
	ds_write2_b32 v75, v12, v13 offset1:1
	s_waitcnt vmcnt(4)
	ds_write2_b32 v76, v14, v15 offset1:1
	ds_write2_b32 v89, v16, v17 offset1:1
	s_waitcnt vmcnt(3)
	ds_write2_b32 v90, v18, v19 offset1:1
	ds_write2_b32 v91, v20, v21 offset1:1
	s_waitcnt vmcnt(2)
	ds_write2_b32 v92, v22, v23 offset1:1
	ds_write2_b32 v93, v24, v25 offset1:1
	s_waitcnt vmcnt(1)
	ds_write2_b32 v94, v26, v27 offset1:1
	ds_write2_b32 v95, v28, v29 offset1:1
	s_waitcnt vmcnt(0)
	ds_write2_b32 v96, v30, v31 offset1:1
	ds_write2_b32 v97, v32, v33 offset1:1
	s_waitcnt lgkmcnt(0)
	ds_read2_b32 v[2:3], v80 offset1:33
	s_waitcnt lgkmcnt(0)
	v_cvt_pk_bf16_f32 v2, v2, v3
	ds_read2_b32 v[4:5], v80 offset0:66 offset1:99
	v_or_b32_e32 v10, s14, v1
	s_waitcnt lgkmcnt(0)
	v_cvt_pk_bf16_f32 v3, v4, v5
	ds_read2_b32 v[4:5], v80 offset0:132 offset1:165
	v_lshl_add_u64 v[8:9], s[4:5], 1, v[50:51]
	v_lshlrev_b32_e32 v36, 11, v10
	s_waitcnt lgkmcnt(0)
	v_cvt_pk_bf16_f32 v4, v4, v5
	ds_read2_b32 v[6:7], v80 offset0:198 offset1:231
	s_waitcnt lgkmcnt(0)
	v_cvt_pk_bf16_f32 v5, v6, v7
	v_lshl_add_u64 v[10:11], v[8:9], 0, v[36:37]
	ds_read2_b32 v[6:7], v80 offset0:8 offset1:41
	global_store_dwordx4 v[10:11], v[2:5], off
	v_or_b32_e32 v10, s14, v77
	v_lshlrev_b32_e32 v36, 11, v10
	s_waitcnt lgkmcnt(0)
	v_cvt_pk_bf16_f32 v2, v6, v7
	ds_read2_b32 v[4:5], v80 offset0:74 offset1:107
	s_waitcnt lgkmcnt(0)
	v_cvt_pk_bf16_f32 v3, v4, v5
	ds_read2_b32 v[4:5], v80 offset0:140 offset1:173
	s_waitcnt lgkmcnt(0)
	v_cvt_pk_bf16_f32 v4, v4, v5
	ds_read2_b32 v[6:7], v80 offset0:206 offset1:239
	s_waitcnt lgkmcnt(0)
	v_cvt_pk_bf16_f32 v5, v6, v7
	v_lshl_add_u64 v[10:11], v[8:9], 0, v[36:37]
	ds_read2_b32 v[6:7], v80 offset0:16 offset1:49
	global_store_dwordx4 v[10:11], v[2:5], off
	v_or_b32_e32 v10, s14, v78
	v_lshlrev_b32_e32 v36, 11, v10
	s_waitcnt lgkmcnt(0)
	v_cvt_pk_bf16_f32 v2, v6, v7
	ds_read2_b32 v[4:5], v80 offset0:82 offset1:115
	s_waitcnt lgkmcnt(0)
	v_cvt_pk_bf16_f32 v3, v4, v5
	ds_read2_b32 v[4:5], v80 offset0:148 offset1:181
	s_waitcnt lgkmcnt(0)
	v_cvt_pk_bf16_f32 v4, v4, v5
	ds_read2_b32 v[6:7], v80 offset0:214 offset1:247
	s_waitcnt lgkmcnt(0)
	v_cvt_pk_bf16_f32 v5, v6, v7
	v_lshl_add_u64 v[10:11], v[8:9], 0, v[36:37]
	ds_read2_b32 v[6:7], v80 offset0:24 offset1:57
	global_store_dwordx4 v[10:11], v[2:5], off
	s_waitcnt lgkmcnt(0)
	s_nop 0
	v_cvt_pk_bf16_f32 v2, v6, v7
	ds_read2_b32 v[4:5], v80 offset0:90 offset1:123
	s_waitcnt lgkmcnt(0)
	v_cvt_pk_bf16_f32 v3, v4, v5
	ds_read2_b32 v[4:5], v80 offset0:156 offset1:189
	s_waitcnt lgkmcnt(0)
	v_cvt_pk_bf16_f32 v4, v4, v5
	v_or_b32_e32 v5, s14, v79
	ds_read2_b32 v[6:7], v80 offset0:222 offset1:255
	v_lshlrev_b32_e32 v36, 11, v5
	s_waitcnt lgkmcnt(0)
	v_cvt_pk_bf16_f32 v5, v6, v7
	v_lshl_add_u64 v[6:7], v[8:9], 0, v[36:37]
	global_store_dwordx4 v[6:7], v[2:5], off
	s_waitcnt lgkmcnt(0)

.LBB0_101:
	s_andn2_b64 vcc, exec, s[4:5]
	s_cbranch_vccnz .LBB0_10
	s_ashr_i32 s4, s50, 31
	s_lshr_b32 s4, s4, 26
	s_add_i32 s5, s50, s4
	s_lshl_b32 s4, s5, 5
	s_and_b32 s14, s5, 0xffffffc0
	s_and_b32 s4, s4, 0xfffff800
	v_or_b32_e32 v30, s14, v1
	s_sub_i32 s4, s9, s4
	v_or_b32_e32 v4, 8, v30
	v_or_b32_e32 v10, 16, v30
	v_or_b32_e32 v12, 24, v30
	v_or_b32_e32 v18, 32, v30
	v_or_b32_e32 v20, 40, v30
	s_ashr_i32 s5, s4, 31
	v_ashrrev_i32_e32 v31, 31, v30
	v_ashrrev_i32_e32 v5, 31, v4
	v_ashrrev_i32_e32 v11, 31, v10
	v_ashrrev_i32_e32 v13, 31, v12
	v_ashrrev_i32_e32 v19, 31, v18
	v_ashrrev_i32_e32 v21, 31, v20
	v_lshl_add_u64 v[32:33], s[4:5], 2, v[70:71]
	v_lshlrev_b64 v[2:3], 13, v[30:31]
	v_lshlrev_b64 v[4:5], 13, v[4:5]
	v_lshlrev_b64 v[10:11], 13, v[10:11]
	v_lshlrev_b64 v[12:13], 13, v[12:13]
	v_lshlrev_b64 v[18:19], 13, v[18:19]
	v_lshlrev_b64 v[20:21], 13, v[20:21]
	v_lshl_add_u64 v[2:3], v[32:33], 0, v[2:3]
	v_lshl_add_u64 v[6:7], v[32:33], 0, v[4:5]
	v_lshl_add_u64 v[10:11], v[32:33], 0, v[10:11]
	v_lshl_add_u64 v[14:15], v[32:33], 0, v[12:13]
	v_lshl_add_u64 v[18:19], v[32:33], 0, v[18:19]
	v_lshl_add_u64 v[22:23], v[32:33], 0, v[20:21]
	global_load_dwordx4 v[2:5], v[2:3], off nt
	s_nop 0
	global_load_dwordx4 v[6:9], v[6:7], off nt
	s_nop 0
	global_load_dwordx4 v[10:13], v[10:11], off nt
	s_nop 0
	global_load_dwordx4 v[14:17], v[14:15], off nt
	s_nop 0
	global_load_dwordx4 v[18:21], v[18:19], off nt
	s_nop 0
	global_load_dwordx4 v[22:25], v[22:23], off nt
	v_or_b32_e32 v26, 48, v30
	v_ashrrev_i32_e32 v27, 31, v26
	v_lshlrev_b64 v[26:27], 13, v[26:27]
	v_or_b32_e32 v30, 56, v30
	v_lshl_add_u64 v[26:27], v[32:33], 0, v[26:27]
	v_ashrrev_i32_e32 v31, 31, v30
	global_load_dwordx4 v[26:29], v[26:27], off nt
	v_lshlrev_b64 v[30:31], 13, v[30:31]
	v_lshl_add_u64 v[30:31], v[32:33], 0, v[30:31]
	global_load_dwordx4 v[30:33], v[30:31], off nt
	v_add_u32_e32 v36, 0x428, v87
	v_add_u32_e32 v73, 0x840, v87
	v_add_u32_e32 v75, 0x848, v87
	v_add_u32_e32 v76, 0xc60, v87
	v_add_u32_e32 v89, 0xc68, v87
	v_add_u32_e32 v90, 0x1080, v87
	v_add_u32_e32 v91, 0x1088, v87
	v_add_u32_e32 v92, 0x14a0, v87
	v_add_u32_e32 v93, 0x14a8, v87
	v_add_u32_e32 v94, 0x18c0, v87
	v_add_u32_e32 v95, 0x18c8, v87
	v_add_u32_e32 v96, 0x1ce0, v87
	v_add_u32_e32 v97, 0x1ce8, v87
	s_ashr_i32 s15, s14, 31
	s_waitcnt vmcnt(7)
	ds_write2_b32 v87, v2, v3 offset1:1
	ds_write2_b32 v87, v4, v5 offset0:2 offset1:3
	s_waitcnt vmcnt(6)
	ds_write2_b32 v88, v6, v7 offset1:1
	ds_write2_b32 v36, v8, v9 offset1:1
	s_waitcnt vmcnt(5)
	ds_write2_b32 v73, v10, v11 offset1:1
	ds_write2_b32 v75, v12, v13 offset1:1
	s_waitcnt vmcnt(4)
	ds_write2_b32 v76, v14, v15 offset1:1
	ds_write2_b32 v89, v16, v17 offset1:1
	s_waitcnt vmcnt(3)
	ds_write2_b32 v90, v18, v19 offset1:1
	ds_write2_b32 v91, v20, v21 offset1:1
	s_waitcnt vmcnt(2)
	ds_write2_b32 v92, v22, v23 offset1:1
	ds_write2_b32 v93, v24, v25 offset1:1
	s_waitcnt vmcnt(1)
	ds_write2_b32 v94, v26, v27 offset1:1
	ds_write2_b32 v95, v28, v29 offset1:1
	s_waitcnt vmcnt(0)
	ds_write2_b32 v96, v30, v31 offset1:1
	ds_write2_b32 v97, v32, v33 offset1:1
	s_waitcnt lgkmcnt(0)
	v_add_u32_e32 v10, s4, v1
	ds_read2_b32 v[2:3], v80 offset1:33
	v_ashrrev_i32_e32 v11, 31, v10
	s_waitcnt lgkmcnt(0)
	v_cvt_pk_bf16_f32 v2, v2, v3
	ds_read2_b32 v[4:5], v80 offset0:66 offset1:99
	v_lshl_add_u64 v[8:9], s[14:15], 1, v[52:53]
	v_lshlrev_b64 v[12:13], 11, v[10:11]
	s_waitcnt lgkmcnt(0)
	v_cvt_pk_bf16_f32 v3, v4, v5
	ds_read2_b32 v[4:5], v80 offset0:132 offset1:165
	v_lshl_add_u64 v[12:13], v[8:9], 0, v[12:13]
	s_waitcnt lgkmcnt(0)
	v_cvt_pk_bf16_f32 v4, v4, v5
	ds_read2_b32 v[6:7], v80 offset0:198 offset1:231
	s_waitcnt lgkmcnt(0)
	v_cvt_pk_bf16_f32 v5, v6, v7
	global_store_dwordx4 v[12:13], v[2:5], off
	v_add_u32_e32 v12, 8, v10
	v_ashrrev_i32_e32 v13, 31, v12
	ds_read2_b32 v[6:7], v80 offset0:8 offset1:41
	s_waitcnt lgkmcnt(0)
	v_cvt_pk_bf16_f32 v2, v6, v7
	ds_read2_b32 v[4:5], v80 offset0:74 offset1:107
	v_lshlrev_b64 v[12:13], 11, v[12:13]
	s_waitcnt lgkmcnt(0)
	v_cvt_pk_bf16_f32 v3, v4, v5
	ds_read2_b32 v[4:5], v80 offset0:140 offset1:173
	v_lshl_add_u64 v[12:13], v[8:9], 0, v[12:13]
	s_waitcnt lgkmcnt(0)
	v_cvt_pk_bf16_f32 v4, v4, v5
	ds_read2_b32 v[6:7], v80 offset0:206 offset1:239
	s_waitcnt lgkmcnt(0)
	v_cvt_pk_bf16_f32 v5, v6, v7
	global_store_dwordx4 v[12:13], v[2:5], off
	v_add_u32_e32 v12, 16, v10
	ds_read2_b32 v[6:7], v80 offset0:16 offset1:49
	s_waitcnt lgkmcnt(0)
	v_cvt_pk_bf16_f32 v2, v6, v7
	ds_read2_b32 v[4:5], v80 offset0:82 offset1:115
	v_ashrrev_i32_e32 v13, 31, v12
	s_waitcnt lgkmcnt(0)
	v_cvt_pk_bf16_f32 v3, v4, v5
	ds_read2_b32 v[4:5], v80 offset0:148 offset1:181
	v_lshlrev_b64 v[12:13], 11, v[12:13]
	s_waitcnt lgkmcnt(0)
	v_cvt_pk_bf16_f32 v4, v4, v5
	ds_read2_b32 v[6:7], v80 offset0:214 offset1:247
	s_waitcnt lgkmcnt(0)
	v_cvt_pk_bf16_f32 v5, v6, v7
	v_lshl_add_u64 v[12:13], v[8:9], 0, v[12:13]
	ds_read2_b32 v[6:7], v80 offset0:24 offset1:57
	global_store_dwordx4 v[12:13], v[2:5], off
	v_add_u32_e32 v10, 24, v10
	v_ashrrev_i32_e32 v11, 31, v10
	s_waitcnt lgkmcnt(0)
	v_cvt_pk_bf16_f32 v2, v6, v7
	ds_read2_b32 v[4:5], v80 offset0:90 offset1:123
	s_waitcnt lgkmcnt(0)
	v_cvt_pk_bf16_f32 v3, v4, v5
	ds_read2_b32 v[4:5], v80 offset0:156 offset1:189
	s_waitcnt lgkmcnt(0)
	v_cvt_pk_bf16_f32 v4, v4, v5
	ds_read2_b32 v[6:7], v80 offset0:222 offset1:255
	v_lshlrev_b64 v[10:11], 11, v[10:11]
	s_waitcnt lgkmcnt(0)
	v_cvt_pk_bf16_f32 v5, v6, v7
	v_lshl_add_u64 v[6:7], v[8:9], 0, v[10:11]
	global_store_dwordx4 v[6:7], v[2:5], off
	s_waitcnt lgkmcnt(0)
	s_branch .LBB0_10
